# gate epilogue: packed v_pk_mul_f32 for the log2e scaling (on top of EpiWo rewrite, in_proj epilogue trims, C=0 first trip)
# baseline (speedup 1.0000x reference)
.LBB0_345:
	s_and_b64 vcc, exec, s[8:9]
	s_cbranch_vccz .LBB0_366
	s_lshl_b32 s9, s87, 2
	s_add_i32 s0, s87, -16
	s_lshl_b32 s8, s88, 4
	s_and_b32 s9, s9, 12
	s_or_b32 s8, s9, s8
	s_lshr_b32 s0, s0, 2
	s_add_i32 s8, s8, s0
	s_ashr_i32 s9, s8, 31
	s_lshl_b64 s[8:9], s[8:9], 16
	v_lshl_add_u64 v[0:1], v[190:191], 0, s[8:9]
	s_mov_b64 s[8:9], 0x1000
	v_lshl_add_u64 v[26:27], v[0:1], 0, s[8:9]
	v_mov_b32_e32 v28, 0xbfb8aa3b
	v_mov_b32_e32 v29, 0xbfb8aa3b
	v_pk_mul_f32 v[2:3], v[162:163], v[28:29]
	v_pk_mul_f32 v[4:5], v[164:165], v[28:29]
	v_pk_mul_f32 v[6:7], v[158:159], v[28:29]
	v_pk_mul_f32 v[8:9], v[160:161], v[28:29]
	v_pk_mul_f32 v[10:11], v[154:155], v[28:29]
	v_pk_mul_f32 v[12:13], v[156:157], v[28:29]
	v_pk_mul_f32 v[14:15], v[150:151], v[28:29]
	v_pk_mul_f32 v[16:17], v[152:153], v[28:29]
	v_exp_f32_e32 v2, v2
	v_exp_f32_e32 v3, v3
	v_exp_f32_e32 v4, v4
	v_exp_f32_e32 v5, v5
	v_exp_f32_e32 v6, v6
	v_exp_f32_e32 v7, v7
	v_exp_f32_e32 v8, v8
	v_exp_f32_e32 v9, v9
	v_exp_f32_e32 v10, v10
	v_exp_f32_e32 v11, v11
	v_exp_f32_e32 v12, v12
	v_exp_f32_e32 v13, v13
	v_exp_f32_e32 v14, v14
	v_exp_f32_e32 v15, v15
	v_exp_f32_e32 v16, v16
	v_exp_f32_e32 v17, v17
	v_fma_f32 v2, v2, v217, v217 clamp
	v_fma_f32 v3, v3, v217, v217 clamp
	v_fma_f32 v4, v4, v217, v217 clamp
	v_fma_f32 v5, v5, v217, v217 clamp
	v_fma_f32 v6, v6, v217, v217 clamp
	v_fma_f32 v7, v7, v217, v217 clamp
	v_fma_f32 v8, v8, v217, v217 clamp
	v_fma_f32 v9, v9, v217, v217 clamp
	v_fma_f32 v10, v10, v217, v217 clamp
	v_fma_f32 v11, v11, v217, v217 clamp
	v_fma_f32 v12, v12, v217, v217 clamp
	v_fma_f32 v13, v13, v217, v217 clamp
	v_fma_f32 v14, v14, v217, v217 clamp
	v_fma_f32 v15, v15, v217, v217 clamp
	v_fma_f32 v16, v16, v217, v217 clamp
	v_fma_f32 v17, v17, v217, v217 clamp
	v_rcp_f32_e32 v2, v2
	v_rcp_f32_e32 v3, v3
	v_rcp_f32_e32 v4, v4
	v_rcp_f32_e32 v5, v5
	v_rcp_f32_e32 v6, v6
	v_rcp_f32_e32 v7, v7
	v_rcp_f32_e32 v8, v8
	v_rcp_f32_e32 v9, v9
	v_rcp_f32_e32 v10, v10
	v_rcp_f32_e32 v11, v11
	v_rcp_f32_e32 v12, v12
	v_rcp_f32_e32 v13, v13
	v_rcp_f32_e32 v14, v14
	v_rcp_f32_e32 v15, v15
	v_rcp_f32_e32 v16, v16
	v_rcp_f32_e32 v17, v17
	v_cvt_pk_u8_f32 v18, v2, 0, 0
	v_cvt_pk_u8_f32 v19, v6, 0, 0
	v_cvt_pk_u8_f32 v20, v10, 0, 0
	v_cvt_pk_u8_f32 v21, v14, 0, 0
	v_cvt_pk_u8_f32 v18, v3, 1, v18
	v_cvt_pk_u8_f32 v19, v7, 1, v19
	v_cvt_pk_u8_f32 v20, v11, 1, v20
	v_cvt_pk_u8_f32 v21, v15, 1, v21
	v_cvt_pk_u8_f32 v18, v4, 2, v18
	v_cvt_pk_u8_f32 v19, v8, 2, v19
	v_cvt_pk_u8_f32 v20, v12, 2, v20
	v_cvt_pk_u8_f32 v21, v16, 2, v21
	v_cvt_pk_u8_f32 v18, v5, 3, v18
	v_cvt_pk_u8_f32 v19, v9, 3, v19
	v_cvt_pk_u8_f32 v20, v13, 3, v20
	v_cvt_pk_u8_f32 v21, v17, 3, v21
	global_store_dwordx4 v[0:1], v[18:21], off nt
	v_pk_mul_f32 v[2:3], v[146:147], v[28:29]
	v_pk_mul_f32 v[4:5], v[148:149], v[28:29]
	v_pk_mul_f32 v[6:7], v[142:143], v[28:29]
	v_pk_mul_f32 v[8:9], v[144:145], v[28:29]
	v_pk_mul_f32 v[10:11], v[138:139], v[28:29]
	v_pk_mul_f32 v[12:13], v[140:141], v[28:29]
	v_pk_mul_f32 v[14:15], v[134:135], v[28:29]
	v_pk_mul_f32 v[16:17], v[136:137], v[28:29]
	v_exp_f32_e32 v2, v2
	v_exp_f32_e32 v3, v3
	v_exp_f32_e32 v4, v4
	v_exp_f32_e32 v5, v5
	v_exp_f32_e32 v6, v6
	v_exp_f32_e32 v7, v7
	v_exp_f32_e32 v8, v8
	v_exp_f32_e32 v9, v9
	v_exp_f32_e32 v10, v10
	v_exp_f32_e32 v11, v11
	v_exp_f32_e32 v12, v12
	v_exp_f32_e32 v13, v13
	v_exp_f32_e32 v14, v14
	v_exp_f32_e32 v15, v15
	v_exp_f32_e32 v16, v16
	v_exp_f32_e32 v17, v17
	v_fma_f32 v2, v2, v217, v217 clamp
	v_fma_f32 v3, v3, v217, v217 clamp
	v_fma_f32 v4, v4, v217, v217 clamp
	v_fma_f32 v5, v5, v217, v217 clamp
	v_fma_f32 v6, v6, v217, v217 clamp
	v_fma_f32 v7, v7, v217, v217 clamp
	v_fma_f32 v8, v8, v217, v217 clamp
	v_fma_f32 v9, v9, v217, v217 clamp
	v_fma_f32 v10, v10, v217, v217 clamp
	v_fma_f32 v11, v11, v217, v217 clamp
	v_fma_f32 v12, v12, v217, v217 clamp
	v_fma_f32 v13, v13, v217, v217 clamp
	v_fma_f32 v14, v14, v217, v217 clamp
	v_fma_f32 v15, v15, v217, v217 clamp
	v_fma_f32 v16, v16, v217, v217 clamp
	v_fma_f32 v17, v17, v217, v217 clamp
	v_rcp_f32_e32 v2, v2
	v_rcp_f32_e32 v3, v3
	v_rcp_f32_e32 v4, v4
	v_rcp_f32_e32 v5, v5
	v_rcp_f32_e32 v6, v6
	v_rcp_f32_e32 v7, v7
	v_rcp_f32_e32 v8, v8
	v_rcp_f32_e32 v9, v9
	v_rcp_f32_e32 v10, v10
	v_rcp_f32_e32 v11, v11
	v_rcp_f32_e32 v12, v12
	v_rcp_f32_e32 v13, v13
	v_rcp_f32_e32 v14, v14
	v_rcp_f32_e32 v15, v15
	v_rcp_f32_e32 v16, v16
	v_rcp_f32_e32 v17, v17
	v_cvt_pk_u8_f32 v22, v2, 0, 0
	v_cvt_pk_u8_f32 v23, v6, 0, 0
	v_cvt_pk_u8_f32 v24, v10, 0, 0
	v_cvt_pk_u8_f32 v25, v14, 0, 0
	v_cvt_pk_u8_f32 v22, v3, 1, v22
	v_cvt_pk_u8_f32 v23, v7, 1, v23
	v_cvt_pk_u8_f32 v24, v11, 1, v24
	v_cvt_pk_u8_f32 v25, v15, 1, v25
	v_cvt_pk_u8_f32 v22, v4, 2, v22
	v_cvt_pk_u8_f32 v23, v8, 2, v23
	v_cvt_pk_u8_f32 v24, v12, 2, v24
	v_cvt_pk_u8_f32 v25, v16, 2, v25
	v_cvt_pk_u8_f32 v22, v5, 3, v22
	v_cvt_pk_u8_f32 v23, v9, 3, v23
	v_cvt_pk_u8_f32 v24, v13, 3, v24
	v_cvt_pk_u8_f32 v25, v17, 3, v25
	global_store_dwordx4 v[0:1], v[22:25], off offset:1024 nt
	v_pk_mul_f32 v[2:3], v[130:131], v[28:29]
	v_pk_mul_f32 v[4:5], v[132:133], v[28:29]
	v_pk_mul_f32 v[6:7], v[126:127], v[28:29]
	v_pk_mul_f32 v[8:9], v[128:129], v[28:29]
	v_pk_mul_f32 v[10:11], v[122:123], v[28:29]
	v_pk_mul_f32 v[12:13], v[124:125], v[28:29]
	v_pk_mul_f32 v[14:15], v[118:119], v[28:29]
	v_pk_mul_f32 v[16:17], v[120:121], v[28:29]
	v_exp_f32_e32 v2, v2
	v_exp_f32_e32 v3, v3
	v_exp_f32_e32 v4, v4
	v_exp_f32_e32 v5, v5
	v_exp_f32_e32 v6, v6
	v_exp_f32_e32 v7, v7
	v_exp_f32_e32 v8, v8
	v_exp_f32_e32 v9, v9
	v_exp_f32_e32 v10, v10
	v_exp_f32_e32 v11, v11
	v_exp_f32_e32 v12, v12
	v_exp_f32_e32 v13, v13
	v_exp_f32_e32 v14, v14
	v_exp_f32_e32 v15, v15
	v_exp_f32_e32 v16, v16
	v_exp_f32_e32 v17, v17
	v_fma_f32 v2, v2, v217, v217 clamp
	v_fma_f32 v3, v3, v217, v217 clamp
	v_fma_f32 v4, v4, v217, v217 clamp
	v_fma_f32 v5, v5, v217, v217 clamp
	v_fma_f32 v6, v6, v217, v217 clamp
	v_fma_f32 v7, v7, v217, v217 clamp
	v_fma_f32 v8, v8, v217, v217 clamp
	v_fma_f32 v9, v9, v217, v217 clamp
	v_fma_f32 v10, v10, v217, v217 clamp
	v_fma_f32 v11, v11, v217, v217 clamp
	v_fma_f32 v12, v12, v217, v217 clamp
	v_fma_f32 v13, v13, v217, v217 clamp
	v_fma_f32 v14, v14, v217, v217 clamp
	v_fma_f32 v15, v15, v217, v217 clamp
	v_fma_f32 v16, v16, v217, v217 clamp
	v_fma_f32 v17, v17, v217, v217 clamp
	v_rcp_f32_e32 v2, v2
	v_rcp_f32_e32 v3, v3
	v_rcp_f32_e32 v4, v4
	v_rcp_f32_e32 v5, v5
	v_rcp_f32_e32 v6, v6
	v_rcp_f32_e32 v7, v7
	v_rcp_f32_e32 v8, v8
	v_rcp_f32_e32 v9, v9
	v_rcp_f32_e32 v10, v10
	v_rcp_f32_e32 v11, v11
	v_rcp_f32_e32 v12, v12
	v_rcp_f32_e32 v13, v13
	v_rcp_f32_e32 v14, v14
	v_rcp_f32_e32 v15, v15
	v_rcp_f32_e32 v16, v16
	v_rcp_f32_e32 v17, v17
	v_cvt_pk_u8_f32 v18, v2, 0, 0
	v_cvt_pk_u8_f32 v19, v6, 0, 0
	v_cvt_pk_u8_f32 v20, v10, 0, 0
	v_cvt_pk_u8_f32 v21, v14, 0, 0
	v_cvt_pk_u8_f32 v18, v3, 1, v18
	v_cvt_pk_u8_f32 v19, v7, 1, v19
	v_cvt_pk_u8_f32 v20, v11, 1, v20
	v_cvt_pk_u8_f32 v21, v15, 1, v21
	v_cvt_pk_u8_f32 v18, v4, 2, v18
	v_cvt_pk_u8_f32 v19, v8, 2, v19
	v_cvt_pk_u8_f32 v20, v12, 2, v20
	v_cvt_pk_u8_f32 v21, v16, 2, v21
	v_cvt_pk_u8_f32 v18, v5, 3, v18
	v_cvt_pk_u8_f32 v19, v9, 3, v19
	v_cvt_pk_u8_f32 v20, v13, 3, v20
	v_cvt_pk_u8_f32 v21, v17, 3, v21
	global_store_dwordx4 v[0:1], v[18:21], off offset:2048 nt
	v_pk_mul_f32 v[2:3], v[114:115], v[28:29]
	v_pk_mul_f32 v[4:5], v[116:117], v[28:29]
	v_pk_mul_f32 v[6:7], v[110:111], v[28:29]
	v_pk_mul_f32 v[8:9], v[112:113], v[28:29]
	v_pk_mul_f32 v[10:11], v[106:107], v[28:29]
	v_pk_mul_f32 v[12:13], v[108:109], v[28:29]
	v_pk_mul_f32 v[14:15], v[102:103], v[28:29]
	v_pk_mul_f32 v[16:17], v[104:105], v[28:29]
	v_exp_f32_e32 v2, v2
	v_exp_f32_e32 v3, v3
	v_exp_f32_e32 v4, v4
	v_exp_f32_e32 v5, v5
	v_exp_f32_e32 v6, v6
	v_exp_f32_e32 v7, v7
	v_exp_f32_e32 v8, v8
	v_exp_f32_e32 v9, v9
	v_exp_f32_e32 v10, v10
	v_exp_f32_e32 v11, v11
	v_exp_f32_e32 v12, v12
	v_exp_f32_e32 v13, v13
	v_exp_f32_e32 v14, v14
	v_exp_f32_e32 v15, v15
	v_exp_f32_e32 v16, v16
	v_exp_f32_e32 v17, v17
	v_fma_f32 v2, v2, v217, v217 clamp
	v_fma_f32 v3, v3, v217, v217 clamp
	v_fma_f32 v4, v4, v217, v217 clamp
	v_fma_f32 v5, v5, v217, v217 clamp
	v_fma_f32 v6, v6, v217, v217 clamp
	v_fma_f32 v7, v7, v217, v217 clamp
	v_fma_f32 v8, v8, v217, v217 clamp
	v_fma_f32 v9, v9, v217, v217 clamp
	v_fma_f32 v10, v10, v217, v217 clamp
	v_fma_f32 v11, v11, v217, v217 clamp
	v_fma_f32 v12, v12, v217, v217 clamp
	v_fma_f32 v13, v13, v217, v217 clamp
	v_fma_f32 v14, v14, v217, v217 clamp
	v_fma_f32 v15, v15, v217, v217 clamp
	v_fma_f32 v16, v16, v217, v217 clamp
	v_fma_f32 v17, v17, v217, v217 clamp
	v_rcp_f32_e32 v2, v2
	v_rcp_f32_e32 v3, v3
	v_rcp_f32_e32 v4, v4
	v_rcp_f32_e32 v5, v5
	v_rcp_f32_e32 v6, v6
	v_rcp_f32_e32 v7, v7
	v_rcp_f32_e32 v8, v8
	v_rcp_f32_e32 v9, v9
	v_rcp_f32_e32 v10, v10
	v_rcp_f32_e32 v11, v11
	v_rcp_f32_e32 v12, v12
	v_rcp_f32_e32 v13, v13
	v_rcp_f32_e32 v14, v14
	v_rcp_f32_e32 v15, v15
	v_rcp_f32_e32 v16, v16
	v_rcp_f32_e32 v17, v17
	v_cvt_pk_u8_f32 v22, v2, 0, 0
	v_cvt_pk_u8_f32 v23, v6, 0, 0
	v_cvt_pk_u8_f32 v24, v10, 0, 0
	v_cvt_pk_u8_f32 v25, v14, 0, 0
	v_cvt_pk_u8_f32 v22, v3, 1, v22
	v_cvt_pk_u8_f32 v23, v7, 1, v23
	v_cvt_pk_u8_f32 v24, v11, 1, v24
	v_cvt_pk_u8_f32 v25, v15, 1, v25
	v_cvt_pk_u8_f32 v22, v4, 2, v22
	v_cvt_pk_u8_f32 v23, v8, 2, v23
	v_cvt_pk_u8_f32 v24, v12, 2, v24
	v_cvt_pk_u8_f32 v25, v16, 2, v25
	v_cvt_pk_u8_f32 v22, v5, 3, v22
	v_cvt_pk_u8_f32 v23, v9, 3, v23
	v_cvt_pk_u8_f32 v24, v13, 3, v24
	v_cvt_pk_u8_f32 v25, v17, 3, v25
	global_store_dwordx4 v[0:1], v[22:25], off offset:3072 nt
	v_pk_mul_f32 v[2:3], v[98:99], v[28:29]
	v_pk_mul_f32 v[4:5], v[100:101], v[28:29]
	v_pk_mul_f32 v[6:7], v[94:95], v[28:29]
	v_pk_mul_f32 v[8:9], v[96:97], v[28:29]
	v_pk_mul_f32 v[10:11], v[90:91], v[28:29]
	v_pk_mul_f32 v[12:13], v[92:93], v[28:29]
	v_pk_mul_f32 v[14:15], v[86:87], v[28:29]
	v_pk_mul_f32 v[16:17], v[88:89], v[28:29]
	v_exp_f32_e32 v2, v2
	v_exp_f32_e32 v3, v3
	v_exp_f32_e32 v4, v4
	v_exp_f32_e32 v5, v5
	v_exp_f32_e32 v6, v6
	v_exp_f32_e32 v7, v7
	v_exp_f32_e32 v8, v8
	v_exp_f32_e32 v9, v9
	v_exp_f32_e32 v10, v10
	v_exp_f32_e32 v11, v11
	v_exp_f32_e32 v12, v12
	v_exp_f32_e32 v13, v13
	v_exp_f32_e32 v14, v14
	v_exp_f32_e32 v15, v15
	v_exp_f32_e32 v16, v16
	v_exp_f32_e32 v17, v17
	v_fma_f32 v2, v2, v217, v217 clamp
	v_fma_f32 v3, v3, v217, v217 clamp
	v_fma_f32 v4, v4, v217, v217 clamp
	v_fma_f32 v5, v5, v217, v217 clamp
	v_fma_f32 v6, v6, v217, v217 clamp
	v_fma_f32 v7, v7, v217, v217 clamp
	v_fma_f32 v8, v8, v217, v217 clamp
	v_fma_f32 v9, v9, v217, v217 clamp
	v_fma_f32 v10, v10, v217, v217 clamp
	v_fma_f32 v11, v11, v217, v217 clamp
	v_fma_f32 v12, v12, v217, v217 clamp
	v_fma_f32 v13, v13, v217, v217 clamp
	v_fma_f32 v14, v14, v217, v217 clamp
	v_fma_f32 v15, v15, v217, v217 clamp
	v_fma_f32 v16, v16, v217, v217 clamp
	v_fma_f32 v17, v17, v217, v217 clamp
	v_rcp_f32_e32 v2, v2
	v_rcp_f32_e32 v3, v3
	v_rcp_f32_e32 v4, v4
	v_rcp_f32_e32 v5, v5
	v_rcp_f32_e32 v6, v6
	v_rcp_f32_e32 v7, v7
	v_rcp_f32_e32 v8, v8
	v_rcp_f32_e32 v9, v9
	v_rcp_f32_e32 v10, v10
	v_rcp_f32_e32 v11, v11
	v_rcp_f32_e32 v12, v12
	v_rcp_f32_e32 v13, v13
	v_rcp_f32_e32 v14, v14
	v_rcp_f32_e32 v15, v15
	v_rcp_f32_e32 v16, v16
	v_rcp_f32_e32 v17, v17
	v_cvt_pk_u8_f32 v18, v2, 0, 0
	v_cvt_pk_u8_f32 v19, v6, 0, 0
	v_cvt_pk_u8_f32 v20, v10, 0, 0
	v_cvt_pk_u8_f32 v21, v14, 0, 0
	v_cvt_pk_u8_f32 v18, v3, 1, v18
	v_cvt_pk_u8_f32 v19, v7, 1, v19
	v_cvt_pk_u8_f32 v20, v11, 1, v20
	v_cvt_pk_u8_f32 v21, v15, 1, v21
	v_cvt_pk_u8_f32 v18, v4, 2, v18
	v_cvt_pk_u8_f32 v19, v8, 2, v19
	v_cvt_pk_u8_f32 v20, v12, 2, v20
	v_cvt_pk_u8_f32 v21, v16, 2, v21
	v_cvt_pk_u8_f32 v18, v5, 3, v18
	v_cvt_pk_u8_f32 v19, v9, 3, v19
	v_cvt_pk_u8_f32 v20, v13, 3, v20
	v_cvt_pk_u8_f32 v21, v17, 3, v21
	global_store_dwordx4 v[26:27], v[18:21], off nt
	v_pk_mul_f32 v[2:3], v[82:83], v[28:29]
	v_pk_mul_f32 v[4:5], v[84:85], v[28:29]
	v_pk_mul_f32 v[6:7], v[78:79], v[28:29]
	v_pk_mul_f32 v[8:9], v[80:81], v[28:29]
	v_pk_mul_f32 v[10:11], v[74:75], v[28:29]
	v_pk_mul_f32 v[12:13], v[76:77], v[28:29]
	v_pk_mul_f32 v[14:15], v[70:71], v[28:29]
	v_pk_mul_f32 v[16:17], v[72:73], v[28:29]
	v_exp_f32_e32 v2, v2
	v_exp_f32_e32 v3, v3
	v_exp_f32_e32 v4, v4
	v_exp_f32_e32 v5, v5
	v_exp_f32_e32 v6, v6
	v_exp_f32_e32 v7, v7
	v_exp_f32_e32 v8, v8
	v_exp_f32_e32 v9, v9
	v_exp_f32_e32 v10, v10
	v_exp_f32_e32 v11, v11
	v_exp_f32_e32 v12, v12
	v_exp_f32_e32 v13, v13
	v_exp_f32_e32 v14, v14
	v_exp_f32_e32 v15, v15
	v_exp_f32_e32 v16, v16
	v_exp_f32_e32 v17, v17
	v_fma_f32 v2, v2, v217, v217 clamp
	v_fma_f32 v3, v3, v217, v217 clamp
	v_fma_f32 v4, v4, v217, v217 clamp
	v_fma_f32 v5, v5, v217, v217 clamp
	v_fma_f32 v6, v6, v217, v217 clamp
	v_fma_f32 v7, v7, v217, v217 clamp
	v_fma_f32 v8, v8, v217, v217 clamp
	v_fma_f32 v9, v9, v217, v217 clamp
	v_fma_f32 v10, v10, v217, v217 clamp
	v_fma_f32 v11, v11, v217, v217 clamp
	v_fma_f32 v12, v12, v217, v217 clamp
	v_fma_f32 v13, v13, v217, v217 clamp
	v_fma_f32 v14, v14, v217, v217 clamp
	v_fma_f32 v15, v15, v217, v217 clamp
	v_fma_f32 v16, v16, v217, v217 clamp
	v_fma_f32 v17, v17, v217, v217 clamp
	v_rcp_f32_e32 v2, v2
	v_rcp_f32_e32 v3, v3
	v_rcp_f32_e32 v4, v4
	v_rcp_f32_e32 v5, v5
	v_rcp_f32_e32 v6, v6
	v_rcp_f32_e32 v7, v7
	v_rcp_f32_e32 v8, v8
	v_rcp_f32_e32 v9, v9
	v_rcp_f32_e32 v10, v10
	v_rcp_f32_e32 v11, v11
	v_rcp_f32_e32 v12, v12
	v_rcp_f32_e32 v13, v13
	v_rcp_f32_e32 v14, v14
	v_rcp_f32_e32 v15, v15
	v_rcp_f32_e32 v16, v16
	v_rcp_f32_e32 v17, v17
	v_cvt_pk_u8_f32 v22, v2, 0, 0
	v_cvt_pk_u8_f32 v23, v6, 0, 0
	v_cvt_pk_u8_f32 v24, v10, 0, 0
	v_cvt_pk_u8_f32 v25, v14, 0, 0
	v_cvt_pk_u8_f32 v22, v3, 1, v22
	v_cvt_pk_u8_f32 v23, v7, 1, v23
	v_cvt_pk_u8_f32 v24, v11, 1, v24
	v_cvt_pk_u8_f32 v25, v15, 1, v25
	v_cvt_pk_u8_f32 v22, v4, 2, v22
	v_cvt_pk_u8_f32 v23, v8, 2, v23
	v_cvt_pk_u8_f32 v24, v12, 2, v24
	v_cvt_pk_u8_f32 v25, v16, 2, v25
	v_cvt_pk_u8_f32 v22, v5, 3, v22
	v_cvt_pk_u8_f32 v23, v9, 3, v23
	v_cvt_pk_u8_f32 v24, v13, 3, v24
	v_cvt_pk_u8_f32 v25, v17, 3, v25
	global_store_dwordx4 v[26:27], v[22:25], off offset:1024 nt
	v_pk_mul_f32 v[2:3], v[66:67], v[28:29]
	v_pk_mul_f32 v[4:5], v[68:69], v[28:29]
	v_pk_mul_f32 v[6:7], v[62:63], v[28:29]
	v_pk_mul_f32 v[8:9], v[64:65], v[28:29]
	v_pk_mul_f32 v[10:11], v[58:59], v[28:29]
	v_pk_mul_f32 v[12:13], v[60:61], v[28:29]
	v_pk_mul_f32 v[14:15], v[54:55], v[28:29]
	v_pk_mul_f32 v[16:17], v[56:57], v[28:29]
	v_exp_f32_e32 v2, v2
	v_exp_f32_e32 v3, v3
	v_exp_f32_e32 v4, v4
	v_exp_f32_e32 v5, v5
	v_exp_f32_e32 v6, v6
	v_exp_f32_e32 v7, v7
	v_exp_f32_e32 v8, v8
	v_exp_f32_e32 v9, v9
	v_exp_f32_e32 v10, v10
	v_exp_f32_e32 v11, v11
	v_exp_f32_e32 v12, v12
	v_exp_f32_e32 v13, v13
	v_exp_f32_e32 v14, v14
	v_exp_f32_e32 v15, v15
	v_exp_f32_e32 v16, v16
	v_exp_f32_e32 v17, v17
	v_fma_f32 v2, v2, v217, v217 clamp
	v_fma_f32 v3, v3, v217, v217 clamp
	v_fma_f32 v4, v4, v217, v217 clamp
	v_fma_f32 v5, v5, v217, v217 clamp
	v_fma_f32 v6, v6, v217, v217 clamp
	v_fma_f32 v7, v7, v217, v217 clamp
	v_fma_f32 v8, v8, v217, v217 clamp
	v_fma_f32 v9, v9, v217, v217 clamp
	v_fma_f32 v10, v10, v217, v217 clamp
	v_fma_f32 v11, v11, v217, v217 clamp
	v_fma_f32 v12, v12, v217, v217 clamp
	v_fma_f32 v13, v13, v217, v217 clamp
	v_fma_f32 v14, v14, v217, v217 clamp
	v_fma_f32 v15, v15, v217, v217 clamp
	v_fma_f32 v16, v16, v217, v217 clamp
	v_fma_f32 v17, v17, v217, v217 clamp
	v_rcp_f32_e32 v2, v2
	v_rcp_f32_e32 v3, v3
	v_rcp_f32_e32 v4, v4
	v_rcp_f32_e32 v5, v5
	v_rcp_f32_e32 v6, v6
	v_rcp_f32_e32 v7, v7
	v_rcp_f32_e32 v8, v8
	v_rcp_f32_e32 v9, v9
	v_rcp_f32_e32 v10, v10
	v_rcp_f32_e32 v11, v11
	v_rcp_f32_e32 v12, v12
	v_rcp_f32_e32 v13, v13
	v_rcp_f32_e32 v14, v14
	v_rcp_f32_e32 v15, v15
	v_rcp_f32_e32 v16, v16
	v_rcp_f32_e32 v17, v17
	v_cvt_pk_u8_f32 v18, v2, 0, 0
	v_cvt_pk_u8_f32 v19, v6, 0, 0
	v_cvt_pk_u8_f32 v20, v10, 0, 0
	v_cvt_pk_u8_f32 v21, v14, 0, 0
	v_cvt_pk_u8_f32 v18, v3, 1, v18
	v_cvt_pk_u8_f32 v19, v7, 1, v19
	v_cvt_pk_u8_f32 v20, v11, 1, v20
	v_cvt_pk_u8_f32 v21, v15, 1, v21
	v_cvt_pk_u8_f32 v18, v4, 2, v18
	v_cvt_pk_u8_f32 v19, v8, 2, v19
	v_cvt_pk_u8_f32 v20, v12, 2, v20
	v_cvt_pk_u8_f32 v21, v16, 2, v21
	v_cvt_pk_u8_f32 v18, v5, 3, v18
	v_cvt_pk_u8_f32 v19, v9, 3, v19
	v_cvt_pk_u8_f32 v20, v13, 3, v20
	v_cvt_pk_u8_f32 v21, v17, 3, v21
	global_store_dwordx4 v[26:27], v[18:21], off offset:2048 nt
	v_pk_mul_f32 v[2:3], v[50:51], v[28:29]
	v_pk_mul_f32 v[4:5], v[52:53], v[28:29]
	v_pk_mul_f32 v[6:7], v[46:47], v[28:29]
	v_pk_mul_f32 v[8:9], v[48:49], v[28:29]
	v_pk_mul_f32 v[10:11], v[42:43], v[28:29]
	v_pk_mul_f32 v[12:13], v[44:45], v[28:29]
	v_pk_mul_f32 v[14:15], v[38:39], v[28:29]
	v_pk_mul_f32 v[16:17], v[40:41], v[28:29]
	v_exp_f32_e32 v2, v2
	v_exp_f32_e32 v3, v3
	v_exp_f32_e32 v4, v4
	v_exp_f32_e32 v5, v5
	v_exp_f32_e32 v6, v6
	v_exp_f32_e32 v7, v7
	v_exp_f32_e32 v8, v8
	v_exp_f32_e32 v9, v9
	v_exp_f32_e32 v10, v10
	v_exp_f32_e32 v11, v11
	v_exp_f32_e32 v12, v12
	v_exp_f32_e32 v13, v13
	v_exp_f32_e32 v14, v14
	v_exp_f32_e32 v15, v15
	v_exp_f32_e32 v16, v16
	v_exp_f32_e32 v17, v17
	v_fma_f32 v2, v2, v217, v217 clamp
	v_fma_f32 v3, v3, v217, v217 clamp
	v_fma_f32 v4, v4, v217, v217 clamp
	v_fma_f32 v5, v5, v217, v217 clamp
	v_fma_f32 v6, v6, v217, v217 clamp
	v_fma_f32 v7, v7, v217, v217 clamp
	v_fma_f32 v8, v8, v217, v217 clamp
	v_fma_f32 v9, v9, v217, v217 clamp
	v_fma_f32 v10, v10, v217, v217 clamp
	v_fma_f32 v11, v11, v217, v217 clamp
	v_fma_f32 v12, v12, v217, v217 clamp
	v_fma_f32 v13, v13, v217, v217 clamp
	v_fma_f32 v14, v14, v217, v217 clamp
	v_fma_f32 v15, v15, v217, v217 clamp
	v_fma_f32 v16, v16, v217, v217 clamp
	v_fma_f32 v17, v17, v217, v217 clamp
	v_rcp_f32_e32 v2, v2
	v_rcp_f32_e32 v3, v3
	v_rcp_f32_e32 v4, v4
	v_rcp_f32_e32 v5, v5
	v_rcp_f32_e32 v6, v6
	v_rcp_f32_e32 v7, v7
	v_rcp_f32_e32 v8, v8
	v_rcp_f32_e32 v9, v9
	v_rcp_f32_e32 v10, v10
	v_rcp_f32_e32 v11, v11
	v_rcp_f32_e32 v12, v12
	v_rcp_f32_e32 v13, v13
	v_rcp_f32_e32 v14, v14
	v_rcp_f32_e32 v15, v15
	v_rcp_f32_e32 v16, v16
	v_rcp_f32_e32 v17, v17
	v_cvt_pk_u8_f32 v22, v2, 0, 0
	v_cvt_pk_u8_f32 v23, v6, 0, 0
	v_cvt_pk_u8_f32 v24, v10, 0, 0
	v_cvt_pk_u8_f32 v25, v14, 0, 0
	v_cvt_pk_u8_f32 v22, v3, 1, v22
	v_cvt_pk_u8_f32 v23, v7, 1, v23
	v_cvt_pk_u8_f32 v24, v11, 1, v24
	v_cvt_pk_u8_f32 v25, v15, 1, v25
	v_cvt_pk_u8_f32 v22, v4, 2, v22
	v_cvt_pk_u8_f32 v23, v8, 2, v23
	v_cvt_pk_u8_f32 v24, v12, 2, v24
	v_cvt_pk_u8_f32 v25, v16, 2, v25
	v_cvt_pk_u8_f32 v22, v5, 3, v22
	v_cvt_pk_u8_f32 v23, v9, 3, v23
	v_cvt_pk_u8_f32 v24, v13, 3, v24
	v_cvt_pk_u8_f32 v25, v17, 3, v25
	global_store_dwordx4 v[26:27], v[22:25], off offset:3072 nt
	s_andn2_b64 vcc, exec, s[64:65]
	s_mov_b64 s[8:9], -1
	s_cbranch_vccnz .LBB0_310
	s_branch .LBB0_367

.LBB0_517:
	s_and_b64 vcc, exec, s[8:9]
	s_cbranch_vccz .LBB0_538
	s_lshl_b32 s9, s72, 2
	s_add_i32 s0, s72, -16
	s_lshl_b32 s8, s73, 4
	s_and_b32 s9, s9, 12
	s_or_b32 s8, s9, s8
	s_lshr_b32 s0, s0, 2
	s_add_i32 s8, s8, s0
	s_ashr_i32 s9, s8, 31
	s_lshl_b64 s[8:9], s[8:9], 16
	v_lshl_add_u64 v[0:1], v[190:191], 0, s[8:9]
	s_mov_b64 s[8:9], 0x1000
	v_lshl_add_u64 v[26:27], v[0:1], 0, s[8:9]
	v_mov_b32_e32 v28, 0xbfb8aa3b
	v_mov_b32_e32 v29, 0xbfb8aa3b
	v_pk_mul_f32 v[2:3], v[162:163], v[28:29]
	v_pk_mul_f32 v[4:5], v[164:165], v[28:29]
	v_pk_mul_f32 v[6:7], v[158:159], v[28:29]
	v_pk_mul_f32 v[8:9], v[160:161], v[28:29]
	v_pk_mul_f32 v[10:11], v[154:155], v[28:29]
	v_pk_mul_f32 v[12:13], v[156:157], v[28:29]
	v_pk_mul_f32 v[14:15], v[150:151], v[28:29]
	v_pk_mul_f32 v[16:17], v[152:153], v[28:29]
	v_exp_f32_e32 v2, v2
	v_exp_f32_e32 v3, v3
	v_exp_f32_e32 v4, v4
	v_exp_f32_e32 v5, v5
	v_exp_f32_e32 v6, v6
	v_exp_f32_e32 v7, v7
	v_exp_f32_e32 v8, v8
	v_exp_f32_e32 v9, v9
	v_exp_f32_e32 v10, v10
	v_exp_f32_e32 v11, v11
	v_exp_f32_e32 v12, v12
	v_exp_f32_e32 v13, v13
	v_exp_f32_e32 v14, v14
	v_exp_f32_e32 v15, v15
	v_exp_f32_e32 v16, v16
	v_exp_f32_e32 v17, v17
	v_fma_f32 v2, v2, v217, v217 clamp
	v_fma_f32 v3, v3, v217, v217 clamp
	v_fma_f32 v4, v4, v217, v217 clamp
	v_fma_f32 v5, v5, v217, v217 clamp
	v_fma_f32 v6, v6, v217, v217 clamp
	v_fma_f32 v7, v7, v217, v217 clamp
	v_fma_f32 v8, v8, v217, v217 clamp
	v_fma_f32 v9, v9, v217, v217 clamp
	v_fma_f32 v10, v10, v217, v217 clamp
	v_fma_f32 v11, v11, v217, v217 clamp
	v_fma_f32 v12, v12, v217, v217 clamp
	v_fma_f32 v13, v13, v217, v217 clamp
	v_fma_f32 v14, v14, v217, v217 clamp
	v_fma_f32 v15, v15, v217, v217 clamp
	v_fma_f32 v16, v16, v217, v217 clamp
	v_fma_f32 v17, v17, v217, v217 clamp
	v_rcp_f32_e32 v2, v2
	v_rcp_f32_e32 v3, v3
	v_rcp_f32_e32 v4, v4
	v_rcp_f32_e32 v5, v5
	v_rcp_f32_e32 v6, v6
	v_rcp_f32_e32 v7, v7
	v_rcp_f32_e32 v8, v8
	v_rcp_f32_e32 v9, v9
	v_rcp_f32_e32 v10, v10
	v_rcp_f32_e32 v11, v11
	v_rcp_f32_e32 v12, v12
	v_rcp_f32_e32 v13, v13
	v_rcp_f32_e32 v14, v14
	v_rcp_f32_e32 v15, v15
	v_rcp_f32_e32 v16, v16
	v_rcp_f32_e32 v17, v17
	v_cvt_pk_u8_f32 v18, v2, 0, 0
	v_cvt_pk_u8_f32 v19, v6, 0, 0
	v_cvt_pk_u8_f32 v20, v10, 0, 0
	v_cvt_pk_u8_f32 v21, v14, 0, 0
	v_cvt_pk_u8_f32 v18, v3, 1, v18
	v_cvt_pk_u8_f32 v19, v7, 1, v19
	v_cvt_pk_u8_f32 v20, v11, 1, v20
	v_cvt_pk_u8_f32 v21, v15, 1, v21
	v_cvt_pk_u8_f32 v18, v4, 2, v18
	v_cvt_pk_u8_f32 v19, v8, 2, v19
	v_cvt_pk_u8_f32 v20, v12, 2, v20
	v_cvt_pk_u8_f32 v21, v16, 2, v21
	v_cvt_pk_u8_f32 v18, v5, 3, v18
	v_cvt_pk_u8_f32 v19, v9, 3, v19
	v_cvt_pk_u8_f32 v20, v13, 3, v20
	v_cvt_pk_u8_f32 v21, v17, 3, v21
	global_store_dwordx4 v[0:1], v[18:21], off nt
	v_pk_mul_f32 v[2:3], v[146:147], v[28:29]
	v_pk_mul_f32 v[4:5], v[148:149], v[28:29]
	v_pk_mul_f32 v[6:7], v[142:143], v[28:29]
	v_pk_mul_f32 v[8:9], v[144:145], v[28:29]
	v_pk_mul_f32 v[10:11], v[138:139], v[28:29]
	v_pk_mul_f32 v[12:13], v[140:141], v[28:29]
	v_pk_mul_f32 v[14:15], v[134:135], v[28:29]
	v_pk_mul_f32 v[16:17], v[136:137], v[28:29]
	v_exp_f32_e32 v2, v2
	v_exp_f32_e32 v3, v3
	v_exp_f32_e32 v4, v4
	v_exp_f32_e32 v5, v5
	v_exp_f32_e32 v6, v6
	v_exp_f32_e32 v7, v7
	v_exp_f32_e32 v8, v8
	v_exp_f32_e32 v9, v9
	v_exp_f32_e32 v10, v10
	v_exp_f32_e32 v11, v11
	v_exp_f32_e32 v12, v12
	v_exp_f32_e32 v13, v13
	v_exp_f32_e32 v14, v14
	v_exp_f32_e32 v15, v15
	v_exp_f32_e32 v16, v16
	v_exp_f32_e32 v17, v17
	v_fma_f32 v2, v2, v217, v217 clamp
	v_fma_f32 v3, v3, v217, v217 clamp
	v_fma_f32 v4, v4, v217, v217 clamp
	v_fma_f32 v5, v5, v217, v217 clamp
	v_fma_f32 v6, v6, v217, v217 clamp
	v_fma_f32 v7, v7, v217, v217 clamp
	v_fma_f32 v8, v8, v217, v217 clamp
	v_fma_f32 v9, v9, v217, v217 clamp
	v_fma_f32 v10, v10, v217, v217 clamp
	v_fma_f32 v11, v11, v217, v217 clamp
	v_fma_f32 v12, v12, v217, v217 clamp
	v_fma_f32 v13, v13, v217, v217 clamp
	v_fma_f32 v14, v14, v217, v217 clamp
	v_fma_f32 v15, v15, v217, v217 clamp
	v_fma_f32 v16, v16, v217, v217 clamp
	v_fma_f32 v17, v17, v217, v217 clamp
	v_rcp_f32_e32 v2, v2
	v_rcp_f32_e32 v3, v3
	v_rcp_f32_e32 v4, v4
	v_rcp_f32_e32 v5, v5
	v_rcp_f32_e32 v6, v6
	v_rcp_f32_e32 v7, v7
	v_rcp_f32_e32 v8, v8
	v_rcp_f32_e32 v9, v9
	v_rcp_f32_e32 v10, v10
	v_rcp_f32_e32 v11, v11
	v_rcp_f32_e32 v12, v12
	v_rcp_f32_e32 v13, v13
	v_rcp_f32_e32 v14, v14
	v_rcp_f32_e32 v15, v15
	v_rcp_f32_e32 v16, v16
	v_rcp_f32_e32 v17, v17
	v_cvt_pk_u8_f32 v22, v2, 0, 0
	v_cvt_pk_u8_f32 v23, v6, 0, 0
	v_cvt_pk_u8_f32 v24, v10, 0, 0
	v_cvt_pk_u8_f32 v25, v14, 0, 0
	v_cvt_pk_u8_f32 v22, v3, 1, v22
	v_cvt_pk_u8_f32 v23, v7, 1, v23
	v_cvt_pk_u8_f32 v24, v11, 1, v24
	v_cvt_pk_u8_f32 v25, v15, 1, v25
	v_cvt_pk_u8_f32 v22, v4, 2, v22
	v_cvt_pk_u8_f32 v23, v8, 2, v23
	v_cvt_pk_u8_f32 v24, v12, 2, v24
	v_cvt_pk_u8_f32 v25, v16, 2, v25
	v_cvt_pk_u8_f32 v22, v5, 3, v22
	v_cvt_pk_u8_f32 v23, v9, 3, v23
	v_cvt_pk_u8_f32 v24, v13, 3, v24
	v_cvt_pk_u8_f32 v25, v17, 3, v25
	global_store_dwordx4 v[0:1], v[22:25], off offset:1024 nt
	v_pk_mul_f32 v[2:3], v[130:131], v[28:29]
	v_pk_mul_f32 v[4:5], v[132:133], v[28:29]
	v_pk_mul_f32 v[6:7], v[126:127], v[28:29]
	v_pk_mul_f32 v[8:9], v[128:129], v[28:29]
	v_pk_mul_f32 v[10:11], v[122:123], v[28:29]
	v_pk_mul_f32 v[12:13], v[124:125], v[28:29]
	v_pk_mul_f32 v[14:15], v[118:119], v[28:29]
	v_pk_mul_f32 v[16:17], v[120:121], v[28:29]
	v_exp_f32_e32 v2, v2
	v_exp_f32_e32 v3, v3
	v_exp_f32_e32 v4, v4
	v_exp_f32_e32 v5, v5
	v_exp_f32_e32 v6, v6
	v_exp_f32_e32 v7, v7
	v_exp_f32_e32 v8, v8
	v_exp_f32_e32 v9, v9
	v_exp_f32_e32 v10, v10
	v_exp_f32_e32 v11, v11
	v_exp_f32_e32 v12, v12
	v_exp_f32_e32 v13, v13
	v_exp_f32_e32 v14, v14
	v_exp_f32_e32 v15, v15
	v_exp_f32_e32 v16, v16
	v_exp_f32_e32 v17, v17
	v_fma_f32 v2, v2, v217, v217 clamp
	v_fma_f32 v3, v3, v217, v217 clamp
	v_fma_f32 v4, v4, v217, v217 clamp
	v_fma_f32 v5, v5, v217, v217 clamp
	v_fma_f32 v6, v6, v217, v217 clamp
	v_fma_f32 v7, v7, v217, v217 clamp
	v_fma_f32 v8, v8, v217, v217 clamp
	v_fma_f32 v9, v9, v217, v217 clamp
	v_fma_f32 v10, v10, v217, v217 clamp
	v_fma_f32 v11, v11, v217, v217 clamp
	v_fma_f32 v12, v12, v217, v217 clamp
	v_fma_f32 v13, v13, v217, v217 clamp
	v_fma_f32 v14, v14, v217, v217 clamp
	v_fma_f32 v15, v15, v217, v217 clamp
	v_fma_f32 v16, v16, v217, v217 clamp
	v_fma_f32 v17, v17, v217, v217 clamp
	v_rcp_f32_e32 v2, v2
	v_rcp_f32_e32 v3, v3
	v_rcp_f32_e32 v4, v4
	v_rcp_f32_e32 v5, v5
	v_rcp_f32_e32 v6, v6
	v_rcp_f32_e32 v7, v7
	v_rcp_f32_e32 v8, v8
	v_rcp_f32_e32 v9, v9
	v_rcp_f32_e32 v10, v10
	v_rcp_f32_e32 v11, v11
	v_rcp_f32_e32 v12, v12
	v_rcp_f32_e32 v13, v13
	v_rcp_f32_e32 v14, v14
	v_rcp_f32_e32 v15, v15
	v_rcp_f32_e32 v16, v16
	v_rcp_f32_e32 v17, v17
	v_cvt_pk_u8_f32 v18, v2, 0, 0
	v_cvt_pk_u8_f32 v19, v6, 0, 0
	v_cvt_pk_u8_f32 v20, v10, 0, 0
	v_cvt_pk_u8_f32 v21, v14, 0, 0
	v_cvt_pk_u8_f32 v18, v3, 1, v18
	v_cvt_pk_u8_f32 v19, v7, 1, v19
	v_cvt_pk_u8_f32 v20, v11, 1, v20
	v_cvt_pk_u8_f32 v21, v15, 1, v21
	v_cvt_pk_u8_f32 v18, v4, 2, v18
	v_cvt_pk_u8_f32 v19, v8, 2, v19
	v_cvt_pk_u8_f32 v20, v12, 2, v20
	v_cvt_pk_u8_f32 v21, v16, 2, v21
	v_cvt_pk_u8_f32 v18, v5, 3, v18
	v_cvt_pk_u8_f32 v19, v9, 3, v19
	v_cvt_pk_u8_f32 v20, v13, 3, v20
	v_cvt_pk_u8_f32 v21, v17, 3, v21
	global_store_dwordx4 v[0:1], v[18:21], off offset:2048 nt
	v_pk_mul_f32 v[2:3], v[114:115], v[28:29]
	v_pk_mul_f32 v[4:5], v[116:117], v[28:29]
	v_pk_mul_f32 v[6:7], v[110:111], v[28:29]
	v_pk_mul_f32 v[8:9], v[112:113], v[28:29]
	v_pk_mul_f32 v[10:11], v[106:107], v[28:29]
	v_pk_mul_f32 v[12:13], v[108:109], v[28:29]
	v_pk_mul_f32 v[14:15], v[102:103], v[28:29]
	v_pk_mul_f32 v[16:17], v[104:105], v[28:29]
	v_exp_f32_e32 v2, v2
	v_exp_f32_e32 v3, v3
	v_exp_f32_e32 v4, v4
	v_exp_f32_e32 v5, v5
	v_exp_f32_e32 v6, v6
	v_exp_f32_e32 v7, v7
	v_exp_f32_e32 v8, v8
	v_exp_f32_e32 v9, v9
	v_exp_f32_e32 v10, v10
	v_exp_f32_e32 v11, v11
	v_exp_f32_e32 v12, v12
	v_exp_f32_e32 v13, v13
	v_exp_f32_e32 v14, v14
	v_exp_f32_e32 v15, v15
	v_exp_f32_e32 v16, v16
	v_exp_f32_e32 v17, v17
	v_fma_f32 v2, v2, v217, v217 clamp
	v_fma_f32 v3, v3, v217, v217 clamp
	v_fma_f32 v4, v4, v217, v217 clamp
	v_fma_f32 v5, v5, v217, v217 clamp
	v_fma_f32 v6, v6, v217, v217 clamp
	v_fma_f32 v7, v7, v217, v217 clamp
	v_fma_f32 v8, v8, v217, v217 clamp
	v_fma_f32 v9, v9, v217, v217 clamp
	v_fma_f32 v10, v10, v217, v217 clamp
	v_fma_f32 v11, v11, v217, v217 clamp
	v_fma_f32 v12, v12, v217, v217 clamp
	v_fma_f32 v13, v13, v217, v217 clamp
	v_fma_f32 v14, v14, v217, v217 clamp
	v_fma_f32 v15, v15, v217, v217 clamp
	v_fma_f32 v16, v16, v217, v217 clamp
	v_fma_f32 v17, v17, v217, v217 clamp
	v_rcp_f32_e32 v2, v2
	v_rcp_f32_e32 v3, v3
	v_rcp_f32_e32 v4, v4
	v_rcp_f32_e32 v5, v5
	v_rcp_f32_e32 v6, v6
	v_rcp_f32_e32 v7, v7
	v_rcp_f32_e32 v8, v8
	v_rcp_f32_e32 v9, v9
	v_rcp_f32_e32 v10, v10
	v_rcp_f32_e32 v11, v11
	v_rcp_f32_e32 v12, v12
	v_rcp_f32_e32 v13, v13
	v_rcp_f32_e32 v14, v14
	v_rcp_f32_e32 v15, v15
	v_rcp_f32_e32 v16, v16
	v_rcp_f32_e32 v17, v17
	v_cvt_pk_u8_f32 v22, v2, 0, 0
	v_cvt_pk_u8_f32 v23, v6, 0, 0
	v_cvt_pk_u8_f32 v24, v10, 0, 0
	v_cvt_pk_u8_f32 v25, v14, 0, 0
	v_cvt_pk_u8_f32 v22, v3, 1, v22
	v_cvt_pk_u8_f32 v23, v7, 1, v23
	v_cvt_pk_u8_f32 v24, v11, 1, v24
	v_cvt_pk_u8_f32 v25, v15, 1, v25
	v_cvt_pk_u8_f32 v22, v4, 2, v22
	v_cvt_pk_u8_f32 v23, v8, 2, v23
	v_cvt_pk_u8_f32 v24, v12, 2, v24
	v_cvt_pk_u8_f32 v25, v16, 2, v25
	v_cvt_pk_u8_f32 v22, v5, 3, v22
	v_cvt_pk_u8_f32 v23, v9, 3, v23
	v_cvt_pk_u8_f32 v24, v13, 3, v24
	v_cvt_pk_u8_f32 v25, v17, 3, v25
	global_store_dwordx4 v[0:1], v[22:25], off offset:3072 nt
	v_pk_mul_f32 v[2:3], v[98:99], v[28:29]
	v_pk_mul_f32 v[4:5], v[100:101], v[28:29]
	v_pk_mul_f32 v[6:7], v[94:95], v[28:29]
	v_pk_mul_f32 v[8:9], v[96:97], v[28:29]
	v_pk_mul_f32 v[10:11], v[90:91], v[28:29]
	v_pk_mul_f32 v[12:13], v[92:93], v[28:29]
	v_pk_mul_f32 v[14:15], v[86:87], v[28:29]
	v_pk_mul_f32 v[16:17], v[88:89], v[28:29]
	v_exp_f32_e32 v2, v2
	v_exp_f32_e32 v3, v3
	v_exp_f32_e32 v4, v4
	v_exp_f32_e32 v5, v5
	v_exp_f32_e32 v6, v6
	v_exp_f32_e32 v7, v7
	v_exp_f32_e32 v8, v8
	v_exp_f32_e32 v9, v9
	v_exp_f32_e32 v10, v10
	v_exp_f32_e32 v11, v11
	v_exp_f32_e32 v12, v12
	v_exp_f32_e32 v13, v13
	v_exp_f32_e32 v14, v14
	v_exp_f32_e32 v15, v15
	v_exp_f32_e32 v16, v16
	v_exp_f32_e32 v17, v17
	v_fma_f32 v2, v2, v217, v217 clamp
	v_fma_f32 v3, v3, v217, v217 clamp
	v_fma_f32 v4, v4, v217, v217 clamp
	v_fma_f32 v5, v5, v217, v217 clamp
	v_fma_f32 v6, v6, v217, v217 clamp
	v_fma_f32 v7, v7, v217, v217 clamp
	v_fma_f32 v8, v8, v217, v217 clamp
	v_fma_f32 v9, v9, v217, v217 clamp
	v_fma_f32 v10, v10, v217, v217 clamp
	v_fma_f32 v11, v11, v217, v217 clamp
	v_fma_f32 v12, v12, v217, v217 clamp
	v_fma_f32 v13, v13, v217, v217 clamp
	v_fma_f32 v14, v14, v217, v217 clamp
	v_fma_f32 v15, v15, v217, v217 clamp
	v_fma_f32 v16, v16, v217, v217 clamp
	v_fma_f32 v17, v17, v217, v217 clamp
	v_rcp_f32_e32 v2, v2
	v_rcp_f32_e32 v3, v3
	v_rcp_f32_e32 v4, v4
	v_rcp_f32_e32 v5, v5
	v_rcp_f32_e32 v6, v6
	v_rcp_f32_e32 v7, v7
	v_rcp_f32_e32 v8, v8
	v_rcp_f32_e32 v9, v9
	v_rcp_f32_e32 v10, v10
	v_rcp_f32_e32 v11, v11
	v_rcp_f32_e32 v12, v12
	v_rcp_f32_e32 v13, v13
	v_rcp_f32_e32 v14, v14
	v_rcp_f32_e32 v15, v15
	v_rcp_f32_e32 v16, v16
	v_rcp_f32_e32 v17, v17
	v_cvt_pk_u8_f32 v18, v2, 0, 0
	v_cvt_pk_u8_f32 v19, v6, 0, 0
	v_cvt_pk_u8_f32 v20, v10, 0, 0
	v_cvt_pk_u8_f32 v21, v14, 0, 0
	v_cvt_pk_u8_f32 v18, v3, 1, v18
	v_cvt_pk_u8_f32 v19, v7, 1, v19
	v_cvt_pk_u8_f32 v20, v11, 1, v20
	v_cvt_pk_u8_f32 v21, v15, 1, v21
	v_cvt_pk_u8_f32 v18, v4, 2, v18
	v_cvt_pk_u8_f32 v19, v8, 2, v19
	v_cvt_pk_u8_f32 v20, v12, 2, v20
	v_cvt_pk_u8_f32 v21, v16, 2, v21
	v_cvt_pk_u8_f32 v18, v5, 3, v18
	v_cvt_pk_u8_f32 v19, v9, 3, v19
	v_cvt_pk_u8_f32 v20, v13, 3, v20
	v_cvt_pk_u8_f32 v21, v17, 3, v21
	global_store_dwordx4 v[26:27], v[18:21], off nt
	v_pk_mul_f32 v[2:3], v[82:83], v[28:29]
	v_pk_mul_f32 v[4:5], v[84:85], v[28:29]
	v_pk_mul_f32 v[6:7], v[78:79], v[28:29]
	v_pk_mul_f32 v[8:9], v[80:81], v[28:29]
	v_pk_mul_f32 v[10:11], v[74:75], v[28:29]
	v_pk_mul_f32 v[12:13], v[76:77], v[28:29]
	v_pk_mul_f32 v[14:15], v[70:71], v[28:29]
	v_pk_mul_f32 v[16:17], v[72:73], v[28:29]
	v_exp_f32_e32 v2, v2
	v_exp_f32_e32 v3, v3
	v_exp_f32_e32 v4, v4
	v_exp_f32_e32 v5, v5
	v_exp_f32_e32 v6, v6
	v_exp_f32_e32 v7, v7
	v_exp_f32_e32 v8, v8
	v_exp_f32_e32 v9, v9
	v_exp_f32_e32 v10, v10
	v_exp_f32_e32 v11, v11
	v_exp_f32_e32 v12, v12
	v_exp_f32_e32 v13, v13
	v_exp_f32_e32 v14, v14
	v_exp_f32_e32 v15, v15
	v_exp_f32_e32 v16, v16
	v_exp_f32_e32 v17, v17
	v_fma_f32 v2, v2, v217, v217 clamp
	v_fma_f32 v3, v3, v217, v217 clamp
	v_fma_f32 v4, v4, v217, v217 clamp
	v_fma_f32 v5, v5, v217, v217 clamp
	v_fma_f32 v6, v6, v217, v217 clamp
	v_fma_f32 v7, v7, v217, v217 clamp
	v_fma_f32 v8, v8, v217, v217 clamp
	v_fma_f32 v9, v9, v217, v217 clamp
	v_fma_f32 v10, v10, v217, v217 clamp
	v_fma_f32 v11, v11, v217, v217 clamp
	v_fma_f32 v12, v12, v217, v217 clamp
	v_fma_f32 v13, v13, v217, v217 clamp
	v_fma_f32 v14, v14, v217, v217 clamp
	v_fma_f32 v15, v15, v217, v217 clamp
	v_fma_f32 v16, v16, v217, v217 clamp
	v_fma_f32 v17, v17, v217, v217 clamp
	v_rcp_f32_e32 v2, v2
	v_rcp_f32_e32 v3, v3
	v_rcp_f32_e32 v4, v4
	v_rcp_f32_e32 v5, v5
	v_rcp_f32_e32 v6, v6
	v_rcp_f32_e32 v7, v7
	v_rcp_f32_e32 v8, v8
	v_rcp_f32_e32 v9, v9
	v_rcp_f32_e32 v10, v10
	v_rcp_f32_e32 v11, v11
	v_rcp_f32_e32 v12, v12
	v_rcp_f32_e32 v13, v13
	v_rcp_f32_e32 v14, v14
	v_rcp_f32_e32 v15, v15
	v_rcp_f32_e32 v16, v16
	v_rcp_f32_e32 v17, v17
	v_cvt_pk_u8_f32 v22, v2, 0, 0
	v_cvt_pk_u8_f32 v23, v6, 0, 0
	v_cvt_pk_u8_f32 v24, v10, 0, 0
	v_cvt_pk_u8_f32 v25, v14, 0, 0
	v_cvt_pk_u8_f32 v22, v3, 1, v22
	v_cvt_pk_u8_f32 v23, v7, 1, v23
	v_cvt_pk_u8_f32 v24, v11, 1, v24
	v_cvt_pk_u8_f32 v25, v15, 1, v25
	v_cvt_pk_u8_f32 v22, v4, 2, v22
	v_cvt_pk_u8_f32 v23, v8, 2, v23
	v_cvt_pk_u8_f32 v24, v12, 2, v24
	v_cvt_pk_u8_f32 v25, v16, 2, v25
	v_cvt_pk_u8_f32 v22, v5, 3, v22
	v_cvt_pk_u8_f32 v23, v9, 3, v23
	v_cvt_pk_u8_f32 v24, v13, 3, v24
	v_cvt_pk_u8_f32 v25, v17, 3, v25
	global_store_dwordx4 v[26:27], v[22:25], off offset:1024 nt
	v_pk_mul_f32 v[2:3], v[66:67], v[28:29]
	v_pk_mul_f32 v[4:5], v[68:69], v[28:29]
	v_pk_mul_f32 v[6:7], v[62:63], v[28:29]
	v_pk_mul_f32 v[8:9], v[64:65], v[28:29]
	v_pk_mul_f32 v[10:11], v[58:59], v[28:29]
	v_pk_mul_f32 v[12:13], v[60:61], v[28:29]
	v_pk_mul_f32 v[14:15], v[54:55], v[28:29]
	v_pk_mul_f32 v[16:17], v[56:57], v[28:29]
	v_exp_f32_e32 v2, v2
	v_exp_f32_e32 v3, v3
	v_exp_f32_e32 v4, v4
	v_exp_f32_e32 v5, v5
	v_exp_f32_e32 v6, v6
	v_exp_f32_e32 v7, v7
	v_exp_f32_e32 v8, v8
	v_exp_f32_e32 v9, v9
	v_exp_f32_e32 v10, v10
	v_exp_f32_e32 v11, v11
	v_exp_f32_e32 v12, v12
	v_exp_f32_e32 v13, v13
	v_exp_f32_e32 v14, v14
	v_exp_f32_e32 v15, v15
	v_exp_f32_e32 v16, v16
	v_exp_f32_e32 v17, v17
	v_fma_f32 v2, v2, v217, v217 clamp
	v_fma_f32 v3, v3, v217, v217 clamp
	v_fma_f32 v4, v4, v217, v217 clamp
	v_fma_f32 v5, v5, v217, v217 clamp
	v_fma_f32 v6, v6, v217, v217 clamp
	v_fma_f32 v7, v7, v217, v217 clamp
	v_fma_f32 v8, v8, v217, v217 clamp
	v_fma_f32 v9, v9, v217, v217 clamp
	v_fma_f32 v10, v10, v217, v217 clamp
	v_fma_f32 v11, v11, v217, v217 clamp
	v_fma_f32 v12, v12, v217, v217 clamp
	v_fma_f32 v13, v13, v217, v217 clamp
	v_fma_f32 v14, v14, v217, v217 clamp
	v_fma_f32 v15, v15, v217, v217 clamp
	v_fma_f32 v16, v16, v217, v217 clamp
	v_fma_f32 v17, v17, v217, v217 clamp
	v_rcp_f32_e32 v2, v2
	v_rcp_f32_e32 v3, v3
	v_rcp_f32_e32 v4, v4
	v_rcp_f32_e32 v5, v5
	v_rcp_f32_e32 v6, v6
	v_rcp_f32_e32 v7, v7
	v_rcp_f32_e32 v8, v8
	v_rcp_f32_e32 v9, v9
	v_rcp_f32_e32 v10, v10
	v_rcp_f32_e32 v11, v11
	v_rcp_f32_e32 v12, v12
	v_rcp_f32_e32 v13, v13
	v_rcp_f32_e32 v14, v14
	v_rcp_f32_e32 v15, v15
	v_rcp_f32_e32 v16, v16
	v_rcp_f32_e32 v17, v17
	v_cvt_pk_u8_f32 v18, v2, 0, 0
	v_cvt_pk_u8_f32 v19, v6, 0, 0
	v_cvt_pk_u8_f32 v20, v10, 0, 0
	v_cvt_pk_u8_f32 v21, v14, 0, 0
	v_cvt_pk_u8_f32 v18, v3, 1, v18
	v_cvt_pk_u8_f32 v19, v7, 1, v19
	v_cvt_pk_u8_f32 v20, v11, 1, v20
	v_cvt_pk_u8_f32 v21, v15, 1, v21
	v_cvt_pk_u8_f32 v18, v4, 2, v18
	v_cvt_pk_u8_f32 v19, v8, 2, v19
	v_cvt_pk_u8_f32 v20, v12, 2, v20
	v_cvt_pk_u8_f32 v21, v16, 2, v21
	v_cvt_pk_u8_f32 v18, v5, 3, v18
	v_cvt_pk_u8_f32 v19, v9, 3, v19
	v_cvt_pk_u8_f32 v20, v13, 3, v20
	v_cvt_pk_u8_f32 v21, v17, 3, v21
	global_store_dwordx4 v[26:27], v[18:21], off offset:2048 nt
	v_pk_mul_f32 v[2:3], v[50:51], v[28:29]
	v_pk_mul_f32 v[4:5], v[52:53], v[28:29]
	v_pk_mul_f32 v[6:7], v[46:47], v[28:29]
	v_pk_mul_f32 v[8:9], v[48:49], v[28:29]
	v_pk_mul_f32 v[10:11], v[42:43], v[28:29]
	v_pk_mul_f32 v[12:13], v[44:45], v[28:29]
	v_pk_mul_f32 v[14:15], v[38:39], v[28:29]
	v_pk_mul_f32 v[16:17], v[40:41], v[28:29]
	v_exp_f32_e32 v2, v2
	v_exp_f32_e32 v3, v3
	v_exp_f32_e32 v4, v4
	v_exp_f32_e32 v5, v5
	v_exp_f32_e32 v6, v6
	v_exp_f32_e32 v7, v7
	v_exp_f32_e32 v8, v8
	v_exp_f32_e32 v9, v9
	v_exp_f32_e32 v10, v10
	v_exp_f32_e32 v11, v11
	v_exp_f32_e32 v12, v12
	v_exp_f32_e32 v13, v13
	v_exp_f32_e32 v14, v14
	v_exp_f32_e32 v15, v15
	v_exp_f32_e32 v16, v16
	v_exp_f32_e32 v17, v17
	v_fma_f32 v2, v2, v217, v217 clamp
	v_fma_f32 v3, v3, v217, v217 clamp
	v_fma_f32 v4, v4, v217, v217 clamp
	v_fma_f32 v5, v5, v217, v217 clamp
	v_fma_f32 v6, v6, v217, v217 clamp
	v_fma_f32 v7, v7, v217, v217 clamp
	v_fma_f32 v8, v8, v217, v217 clamp
	v_fma_f32 v9, v9, v217, v217 clamp
	v_fma_f32 v10, v10, v217, v217 clamp
	v_fma_f32 v11, v11, v217, v217 clamp
	v_fma_f32 v12, v12, v217, v217 clamp
	v_fma_f32 v13, v13, v217, v217 clamp
	v_fma_f32 v14, v14, v217, v217 clamp
	v_fma_f32 v15, v15, v217, v217 clamp
	v_fma_f32 v16, v16, v217, v217 clamp
	v_fma_f32 v17, v17, v217, v217 clamp
	v_rcp_f32_e32 v2, v2
	v_rcp_f32_e32 v3, v3
	v_rcp_f32_e32 v4, v4
	v_rcp_f32_e32 v5, v5
	v_rcp_f32_e32 v6, v6
	v_rcp_f32_e32 v7, v7
	v_rcp_f32_e32 v8, v8
	v_rcp_f32_e32 v9, v9
	v_rcp_f32_e32 v10, v10
	v_rcp_f32_e32 v11, v11
	v_rcp_f32_e32 v12, v12
	v_rcp_f32_e32 v13, v13
	v_rcp_f32_e32 v14, v14
	v_rcp_f32_e32 v15, v15
	v_rcp_f32_e32 v16, v16
	v_rcp_f32_e32 v17, v17
	v_cvt_pk_u8_f32 v22, v2, 0, 0
	v_cvt_pk_u8_f32 v23, v6, 0, 0
	v_cvt_pk_u8_f32 v24, v10, 0, 0
	v_cvt_pk_u8_f32 v25, v14, 0, 0
	v_cvt_pk_u8_f32 v22, v3, 1, v22
	v_cvt_pk_u8_f32 v23, v7, 1, v23
	v_cvt_pk_u8_f32 v24, v11, 1, v24
	v_cvt_pk_u8_f32 v25, v15, 1, v25
	v_cvt_pk_u8_f32 v22, v4, 2, v22
	v_cvt_pk_u8_f32 v23, v8, 2, v23
	v_cvt_pk_u8_f32 v24, v12, 2, v24
	v_cvt_pk_u8_f32 v25, v16, 2, v25
	v_cvt_pk_u8_f32 v22, v5, 3, v22
	v_cvt_pk_u8_f32 v23, v9, 3, v23
	v_cvt_pk_u8_f32 v24, v13, 3, v24
	v_cvt_pk_u8_f32 v25, v17, 3, v25
	global_store_dwordx4 v[26:27], v[22:25], off offset:3072 nt
	s_andn2_b64 vcc, exec, s[30:31]
	s_mov_b64 s[8:9], -1
	s_cbranch_vccnz .LBB0_473
	s_branch .LBB0_539
